# v24 + attention epilogues: 16x store_dwordx2 -> 8x store_dwordx4 via v_permlane32_swap pairs (doc 7.3)
# baseline (speedup 1.0000x reference)
.LBB0_446:
	ds_bpermute_b32 v1, v202, v208
	v_ashrrev_i32_e32 v195, 31, v194
	v_lshl_add_u64 v[2:3], s[0:1], 0, v[194:195]
	v_readlane_b32 s4, v255, 8
	v_lshlrev_b64 v[2:3], 12, v[2:3]
	s_waitcnt lgkmcnt(0)
	v_add_f32_e32 v1, v208, v1
	v_div_scale_f32 v4, s[0:1], v1, v1, 1.0
	v_rcp_f32_e32 v5, v4
	v_div_scale_f32 v6, vcc, 1.0, v1, 1.0
	v_readlane_b32 s6, v255, 10
	v_fma_f32 v7, -v4, v5, 1.0
	v_fmac_f32_e32 v5, v7, v5
	v_mul_f32_e32 v7, v6, v5
	v_fma_f32 v8, -v4, v7, v6
	v_fmac_f32_e32 v7, v8, v5
	v_fma_f32 v4, -v4, v7, v6
	v_readlane_b32 s7, v255, 11
	v_div_fmas_f32 v4, v4, v5, v7
	v_div_fixup_f32 v4, v4, v1, 1.0
	v_lshl_add_u64 v[2:3], s[6:7], 0, v[2:3]
	v_lshl_add_u64 v[2:3], v[2:3], 0, s[36:37]
	v_lshlrev_b32_e32 v6, 1, v193
	v_mov_b32_e32 v7, v0
	v_lshl_add_u64 v[2:3], v[2:3], 0, v[6:7]
	v_and_b32_e32 v10, 32, v219
	v_lshrrev_b32_e32 v10, 2, v10
	v_mov_b32_e32 v11, v0
	v_lshl_add_u64 v[2:3], v[2:3], 0, v[10:11]
	v_pk_mul_f32 v[10:11], v[64:65], v[4:5] op_sel_hi:[1,0]
	v_pk_mul_f32 v[12:13], v[66:67], v[4:5] op_sel_hi:[1,0]
	v_cvt_pk_bf16_f32 v6, v10, v11
	v_cvt_pk_bf16_f32 v7, v12, v13
	v_pk_mul_f32 v[10:11], v[68:69], v[4:5] op_sel_hi:[1,0]
	v_pk_mul_f32 v[12:13], v[70:71], v[4:5] op_sel_hi:[1,0]
	v_cvt_pk_bf16_f32 v8, v10, v11
	v_cvt_pk_bf16_f32 v9, v12, v13
	s_nop 1
	v_permlane32_swap_b32 v6, v8
	v_permlane32_swap_b32 v7, v9
	global_store_dwordx4 v[2:3], v[6:9], off
	v_pk_mul_f32 v[10:11], v[72:73], v[4:5] op_sel_hi:[1,0]
	v_pk_mul_f32 v[12:13], v[74:75], v[4:5] op_sel_hi:[1,0]
	v_cvt_pk_bf16_f32 v6, v10, v11
	v_cvt_pk_bf16_f32 v7, v12, v13
	v_pk_mul_f32 v[10:11], v[76:77], v[4:5] op_sel_hi:[1,0]
	v_pk_mul_f32 v[12:13], v[78:79], v[4:5] op_sel_hi:[1,0]
	v_cvt_pk_bf16_f32 v8, v10, v11
	v_cvt_pk_bf16_f32 v9, v12, v13
	s_nop 1
	v_permlane32_swap_b32 v6, v8
	v_permlane32_swap_b32 v7, v9
	global_store_dwordx4 v[2:3], v[6:9], off offset:32
	v_pk_mul_f32 v[10:11], v[48:49], v[4:5] op_sel_hi:[1,0]
	v_pk_mul_f32 v[12:13], v[50:51], v[4:5] op_sel_hi:[1,0]
	v_cvt_pk_bf16_f32 v6, v10, v11
	v_cvt_pk_bf16_f32 v7, v12, v13
	v_pk_mul_f32 v[10:11], v[52:53], v[4:5] op_sel_hi:[1,0]
	v_pk_mul_f32 v[12:13], v[54:55], v[4:5] op_sel_hi:[1,0]
	v_cvt_pk_bf16_f32 v8, v10, v11
	v_cvt_pk_bf16_f32 v9, v12, v13
	s_nop 1
	v_permlane32_swap_b32 v6, v8
	v_permlane32_swap_b32 v7, v9
	global_store_dwordx4 v[2:3], v[6:9], off offset:64
	v_pk_mul_f32 v[10:11], v[56:57], v[4:5] op_sel_hi:[1,0]
	v_pk_mul_f32 v[12:13], v[58:59], v[4:5] op_sel_hi:[1,0]
	v_cvt_pk_bf16_f32 v6, v10, v11
	v_cvt_pk_bf16_f32 v7, v12, v13
	v_pk_mul_f32 v[10:11], v[60:61], v[4:5] op_sel_hi:[1,0]
	v_pk_mul_f32 v[12:13], v[62:63], v[4:5] op_sel_hi:[1,0]
	v_cvt_pk_bf16_f32 v8, v10, v11
	v_cvt_pk_bf16_f32 v9, v12, v13
	s_nop 1
	v_permlane32_swap_b32 v6, v8
	v_permlane32_swap_b32 v7, v9
	global_store_dwordx4 v[2:3], v[6:9], off offset:96
	v_pk_mul_f32 v[10:11], v[32:33], v[4:5] op_sel_hi:[1,0]
	v_pk_mul_f32 v[12:13], v[34:35], v[4:5] op_sel_hi:[1,0]
	v_cvt_pk_bf16_f32 v6, v10, v11
	v_cvt_pk_bf16_f32 v7, v12, v13
	v_pk_mul_f32 v[10:11], v[36:37], v[4:5] op_sel_hi:[1,0]
	v_pk_mul_f32 v[12:13], v[38:39], v[4:5] op_sel_hi:[1,0]
	v_cvt_pk_bf16_f32 v8, v10, v11
	v_cvt_pk_bf16_f32 v9, v12, v13
	s_nop 1
	v_permlane32_swap_b32 v6, v8
	v_permlane32_swap_b32 v7, v9
	global_store_dwordx4 v[2:3], v[6:9], off offset:128
	v_pk_mul_f32 v[10:11], v[40:41], v[4:5] op_sel_hi:[1,0]
	v_pk_mul_f32 v[12:13], v[42:43], v[4:5] op_sel_hi:[1,0]
	v_cvt_pk_bf16_f32 v6, v10, v11
	v_cvt_pk_bf16_f32 v7, v12, v13
	v_pk_mul_f32 v[10:11], v[44:45], v[4:5] op_sel_hi:[1,0]
	v_pk_mul_f32 v[12:13], v[46:47], v[4:5] op_sel_hi:[1,0]
	v_cvt_pk_bf16_f32 v8, v10, v11
	v_cvt_pk_bf16_f32 v9, v12, v13
	s_nop 1
	v_permlane32_swap_b32 v6, v8
	v_permlane32_swap_b32 v7, v9
	global_store_dwordx4 v[2:3], v[6:9], off offset:160
	v_pk_mul_f32 v[10:11], v[16:17], v[4:5] op_sel_hi:[1,0]
	v_pk_mul_f32 v[12:13], v[18:19], v[4:5] op_sel_hi:[1,0]
	v_cvt_pk_bf16_f32 v6, v10, v11
	v_cvt_pk_bf16_f32 v7, v12, v13
	v_pk_mul_f32 v[10:11], v[20:21], v[4:5] op_sel_hi:[1,0]
	v_pk_mul_f32 v[12:13], v[22:23], v[4:5] op_sel_hi:[1,0]
	v_cvt_pk_bf16_f32 v8, v10, v11
	v_cvt_pk_bf16_f32 v9, v12, v13
	s_nop 1
	v_permlane32_swap_b32 v6, v8
	v_permlane32_swap_b32 v7, v9
	global_store_dwordx4 v[2:3], v[6:9], off offset:192
	v_pk_mul_f32 v[10:11], v[24:25], v[4:5] op_sel_hi:[1,0]
	v_pk_mul_f32 v[12:13], v[26:27], v[4:5] op_sel_hi:[1,0]
	v_cvt_pk_bf16_f32 v6, v10, v11
	v_cvt_pk_bf16_f32 v7, v12, v13
	v_pk_mul_f32 v[10:11], v[28:29], v[4:5] op_sel_hi:[1,0]
	v_pk_mul_f32 v[12:13], v[30:31], v[4:5] op_sel_hi:[1,0]
	v_cvt_pk_bf16_f32 v8, v10, v11
	v_cvt_pk_bf16_f32 v9, v12, v13
	s_nop 1
	v_permlane32_swap_b32 v6, v8
	v_permlane32_swap_b32 v7, v9
	global_store_dwordx4 v[2:3], v[6:9], off offset:224
	s_add_i32 s23, s23, s96
	s_add_i32 s22, s22, s96
	v_readlane_b32 s5, v255, 9
	s_cmpk_lt_i32 s23, 0x100
	s_cbranch_scc0 .LBB0_443

.LBB0_459:
	v_and_b32_e32 v2, 64, v219
	v_xor_b32_e32 v1, 32, v219
	v_add_u32_e32 v2, 64, v2
	v_cmp_lt_i32_e32 vcc, v1, v2
	v_ashrrev_i32_e32 v195, 31, v194
	v_readlane_b32 s4, v255, 8
	v_cndmask_b32_e32 v1, v219, v1, vcc
	v_lshlrev_b32_e32 v202, 2, v1
	ds_bpermute_b32 v1, v202, v207
	v_readlane_b32 s6, v255, 10
	v_readlane_b32 s7, v255, 11
	s_lshl_b32 s36, s36, 1
	v_mov_b32_e32 v7, v0
	s_waitcnt lgkmcnt(0)
	v_add_f32_e32 v1, v207, v1
	v_div_scale_f32 v2, s[18:19], v1, v1, 1.0
	v_rcp_f32_e32 v3, v2
	v_div_scale_f32 v4, vcc, 1.0, v1, 1.0
	s_mov_b32 s18, 0x20000
	v_fma_f32 v5, -v2, v3, 1.0
	v_fmac_f32_e32 v3, v5, v3
	v_mul_f32_e32 v5, v4, v3
	v_fma_f32 v6, -v2, v5, v4
	v_fmac_f32_e32 v5, v6, v3
	v_fma_f32 v2, -v2, v5, v4
	v_div_fmas_f32 v2, v2, v3, v5
	v_lshl_add_u64 v[4:5], s[0:1], 0, v[194:195]
	v_lshlrev_b64 v[4:5], 12, v[4:5]
	v_lshl_add_u64 v[4:5], s[6:7], 0, v[4:5]
	v_div_fixup_f32 v2, v2, v1, 1.0
	v_lshl_add_u64 v[4:5], v[4:5], 0, s[36:37]
	v_lshlrev_b32_e32 v6, 1, v203
	v_lshl_add_u64 v[4:5], v[4:5], 0, v[6:7]
	v_and_b32_e32 v10, 32, v219
	v_lshrrev_b32_e32 v10, 2, v10
	v_mov_b32_e32 v11, v0
	v_lshl_add_u64 v[4:5], v[4:5], 0, v[10:11]
	v_pk_mul_f32 v[10:11], v[64:65], v[2:3] op_sel_hi:[1,0]
	v_pk_mul_f32 v[12:13], v[66:67], v[2:3] op_sel_hi:[1,0]
	v_cvt_pk_bf16_f32 v6, v10, v11
	v_cvt_pk_bf16_f32 v7, v12, v13
	v_pk_mul_f32 v[10:11], v[68:69], v[2:3] op_sel_hi:[1,0]
	v_pk_mul_f32 v[12:13], v[70:71], v[2:3] op_sel_hi:[1,0]
	v_cvt_pk_bf16_f32 v8, v10, v11
	v_cvt_pk_bf16_f32 v9, v12, v13
	s_nop 1
	v_permlane32_swap_b32 v6, v8
	v_permlane32_swap_b32 v7, v9
	global_store_dwordx4 v[4:5], v[6:9], off
	v_pk_mul_f32 v[10:11], v[72:73], v[2:3] op_sel_hi:[1,0]
	v_pk_mul_f32 v[12:13], v[74:75], v[2:3] op_sel_hi:[1,0]
	v_cvt_pk_bf16_f32 v6, v10, v11
	v_cvt_pk_bf16_f32 v7, v12, v13
	v_pk_mul_f32 v[10:11], v[76:77], v[2:3] op_sel_hi:[1,0]
	v_pk_mul_f32 v[12:13], v[78:79], v[2:3] op_sel_hi:[1,0]
	v_cvt_pk_bf16_f32 v8, v10, v11
	v_cvt_pk_bf16_f32 v9, v12, v13
	s_nop 1
	v_permlane32_swap_b32 v6, v8
	v_permlane32_swap_b32 v7, v9
	global_store_dwordx4 v[4:5], v[6:9], off offset:32
	v_pk_mul_f32 v[10:11], v[48:49], v[2:3] op_sel_hi:[1,0]
	v_pk_mul_f32 v[12:13], v[50:51], v[2:3] op_sel_hi:[1,0]
	v_cvt_pk_bf16_f32 v6, v10, v11
	v_cvt_pk_bf16_f32 v7, v12, v13
	v_pk_mul_f32 v[10:11], v[52:53], v[2:3] op_sel_hi:[1,0]
	v_pk_mul_f32 v[12:13], v[54:55], v[2:3] op_sel_hi:[1,0]
	v_cvt_pk_bf16_f32 v8, v10, v11
	v_cvt_pk_bf16_f32 v9, v12, v13
	s_nop 1
	v_permlane32_swap_b32 v6, v8
	v_permlane32_swap_b32 v7, v9
	global_store_dwordx4 v[4:5], v[6:9], off offset:64
	v_pk_mul_f32 v[10:11], v[56:57], v[2:3] op_sel_hi:[1,0]
	v_pk_mul_f32 v[12:13], v[58:59], v[2:3] op_sel_hi:[1,0]
	v_cvt_pk_bf16_f32 v6, v10, v11
	v_cvt_pk_bf16_f32 v7, v12, v13
	v_pk_mul_f32 v[10:11], v[60:61], v[2:3] op_sel_hi:[1,0]
	v_pk_mul_f32 v[12:13], v[62:63], v[2:3] op_sel_hi:[1,0]
	v_cvt_pk_bf16_f32 v8, v10, v11
	v_cvt_pk_bf16_f32 v9, v12, v13
	s_nop 1
	v_permlane32_swap_b32 v6, v8
	v_permlane32_swap_b32 v7, v9
	global_store_dwordx4 v[4:5], v[6:9], off offset:96
	v_pk_mul_f32 v[10:11], v[32:33], v[2:3] op_sel_hi:[1,0]
	v_pk_mul_f32 v[12:13], v[34:35], v[2:3] op_sel_hi:[1,0]
	v_cvt_pk_bf16_f32 v6, v10, v11
	v_cvt_pk_bf16_f32 v7, v12, v13
	v_pk_mul_f32 v[10:11], v[36:37], v[2:3] op_sel_hi:[1,0]
	v_pk_mul_f32 v[12:13], v[38:39], v[2:3] op_sel_hi:[1,0]
	v_cvt_pk_bf16_f32 v8, v10, v11
	v_cvt_pk_bf16_f32 v9, v12, v13
	s_nop 1
	v_permlane32_swap_b32 v6, v8
	v_permlane32_swap_b32 v7, v9
	global_store_dwordx4 v[4:5], v[6:9], off offset:128
	v_pk_mul_f32 v[10:11], v[40:41], v[2:3] op_sel_hi:[1,0]
	v_pk_mul_f32 v[12:13], v[42:43], v[2:3] op_sel_hi:[1,0]
	v_cvt_pk_bf16_f32 v6, v10, v11
	v_cvt_pk_bf16_f32 v7, v12, v13
	v_pk_mul_f32 v[10:11], v[44:45], v[2:3] op_sel_hi:[1,0]
	v_pk_mul_f32 v[12:13], v[46:47], v[2:3] op_sel_hi:[1,0]
	v_cvt_pk_bf16_f32 v8, v10, v11
	v_cvt_pk_bf16_f32 v9, v12, v13
	s_nop 1
	v_permlane32_swap_b32 v6, v8
	v_permlane32_swap_b32 v7, v9
	global_store_dwordx4 v[4:5], v[6:9], off offset:160
	v_pk_mul_f32 v[10:11], v[16:17], v[2:3] op_sel_hi:[1,0]
	v_pk_mul_f32 v[12:13], v[18:19], v[2:3] op_sel_hi:[1,0]
	v_cvt_pk_bf16_f32 v6, v10, v11
	v_cvt_pk_bf16_f32 v7, v12, v13
	v_pk_mul_f32 v[10:11], v[20:21], v[2:3] op_sel_hi:[1,0]
	v_pk_mul_f32 v[12:13], v[22:23], v[2:3] op_sel_hi:[1,0]
	v_cvt_pk_bf16_f32 v8, v10, v11
	v_cvt_pk_bf16_f32 v9, v12, v13
	s_nop 1
	v_permlane32_swap_b32 v6, v8
	v_permlane32_swap_b32 v7, v9
	global_store_dwordx4 v[4:5], v[6:9], off offset:192
	v_pk_mul_f32 v[10:11], v[24:25], v[2:3] op_sel_hi:[1,0]
	v_pk_mul_f32 v[12:13], v[26:27], v[2:3] op_sel_hi:[1,0]
	v_cvt_pk_bf16_f32 v6, v10, v11
	v_cvt_pk_bf16_f32 v7, v12, v13
	v_pk_mul_f32 v[10:11], v[28:29], v[2:3] op_sel_hi:[1,0]
	v_pk_mul_f32 v[12:13], v[30:31], v[2:3] op_sel_hi:[1,0]
	v_cvt_pk_bf16_f32 v8, v10, v11
	v_cvt_pk_bf16_f32 v9, v12, v13
	s_nop 1
	v_permlane32_swap_b32 v6, v8
	v_permlane32_swap_b32 v7, v9
	global_store_dwordx4 v[4:5], v[6:9], off offset:224
	v_mov_b32_e32 v1, v214
	v_mov_b32_e32 v5, v0
	v_and_b32_e32 v13, 15, v1
	v_and_b32_e32 v15, 7, v1
	v_ashrrev_i32_e32 v12, 4, v1
	v_lshlrev_b32_e32 v2, 3, v13
	v_ashrrev_i32_e32 v14, 3, v1
	v_lshlrev_b32_e32 v3, 3, v15
	v_lshl_or_b32 v2, v12, 11, v2
	v_lshl_or_b32 v4, v14, 6, v3
	v_lshl_or_b32 v6, v14, 13, v3
	v_mov_b32_e32 v3, v0
	v_lshlrev_b64 v[2:3], 1, v[2:3]
	v_lshl_add_u64 v[8:9], s[84:85], 0, v[2:3]
	v_add_co_u32_e32 v10, vcc, s18, v8
	v_lshlrev_b64 v[4:5], 1, v[4:5]
	v_mov_b32_e32 v7, v0
	v_addc_co_u32_e32 v11, vcc, 0, v9, vcc
	global_load_dwordx4 v[112:115], v[8:9], off
	global_load_dwordx4 v[116:119], v[10:11], off
	v_lshl_add_u64 v[8:9], s[80:81], 0, v[4:5]
	v_lshlrev_b64 v[6:7], 1, v[6:7]
	global_load_dwordx4 v[120:123], v[8:9], off
	v_lshl_add_u64 v[8:9], s[82:83], 0, v[6:7]
	s_mov_b32 s18, 0x100000
	global_load_dwordx4 v[124:127], v[8:9], off
	v_add_co_u32_e32 v8, vcc, s18, v8
	v_readfirstlane_b32 s18, v1
	s_ashr_i32 s18, s18, 1
	s_and_b32 s27, s18, 0xffffffe0
	s_add_i32 s27, s27, s25
	s_add_i32 s28, s25, 0x100
	s_ashr_i32 s18, s27, 31
	v_readlane_b32 s5, v255, 9
	v_addc_co_u32_e32 v9, vcc, 0, v9, vcc
	v_and_b32_e32 v16, 31, v1
	s_add_u32 s19, s0, s27
	global_load_dwordx4 v[144:147], v[8:9], off
	v_or_b32_e32 v10, s19, v16
	v_mov_b64_e32 v[8:9], s[4:5]
	s_addc_u32 s25, s1, s18
	v_mad_u64_u32 v[8:9], s[18:19], v10, s24, v[8:9]
	v_bfe_u32 v1, v1, 5, 1
	v_mad_i32_i24 v9, s25, v220, v9
	v_lshl_add_u64 v[10:11], v[8:9], 0, s[36:37]
	v_lshlrev_b32_e32 v192, 4, v1
	v_mov_b32_e32 v193, v0
	v_lshl_add_u64 v[10:11], v[10:11], 0, v[192:193]
	s_lshl_b32 s18, s21, 1
	s_mov_b32 s19, s37
	global_load_dwordx4 v[128:131], v[10:11], off
	global_load_dwordx4 v[132:135], v[10:11], off offset:32
	global_load_dwordx4 v[136:139], v[10:11], off offset:64
	global_load_dwordx4 v[140:143], v[10:11], off offset:96
	global_load_dwordx4 v[148:151], v[10:11], off offset:128
	global_load_dwordx4 v[152:155], v[10:11], off offset:160
	global_load_dwordx4 v[156:159], v[10:11], off offset:192
	global_load_dwordx4 v[160:163], v[10:11], off offset:224
	v_lshl_add_u64 v[8:9], v[8:9], 0, s[18:19]
	v_lshl_add_u64 v[8:9], v[8:9], 0, v[192:193]
	s_movk_i32 s4, 0x1000
	v_add_co_u32_e32 v8, vcc, s4, v8
	s_movk_i32 s18, 0x190
	s_nop 0
	v_addc_co_u32_e32 v9, vcc, 0, v9, vcc
	global_load_dwordx4 v[164:167], v[8:9], off
	global_load_dwordx4 v[168:171], v[8:9], off offset:32
	global_load_dwordx4 v[172:175], v[8:9], off offset:64
	global_load_dwordx4 v[176:179], v[8:9], off offset:96
	v_mul_lo_u32 v8, v12, s18
	v_lshl_add_u32 v203, v13, 4, v8
	v_mul_lo_u32 v8, v14, s18
	s_movk_i32 s18, 0xfef8
	v_mul_lo_u32 v10, v14, s18
	s_movk_i32 s18, 0x108
	v_lshlrev_b32_e32 v195, 3, v1
	s_lshr_b32 s28, s28, 6
	s_or_b32 s29, s27, 31
	v_lshlrev_b32_e32 v193, 2, v1
	v_mul_lo_u32 v1, v14, s18
	v_readlane_b32 s18, v254, 35
	s_add_u32 s18, s18, s20
	v_readlane_b32 s19, v254, 36
	s_addc_u32 s19, s19, s26
	v_add_u32_e32 v9, 0, v203
	v_lshl_add_u64 v[196:197], s[18:19], 0, v[6:7]
	v_readlane_b32 s18, v254, 37
	s_add_u32 s18, s18, s38
	v_readlane_b32 s19, v254, 38
	v_lshl_add_u32 v8, v15, 4, v8
	s_addc_u32 s19, s19, s39
	s_waitcnt vmcnt(16)
	ds_write_b128 v9, v[112:115]
	s_waitcnt vmcnt(15)
	ds_write_b128 v9, v[116:119] offset:12800
	v_add_u32_e32 v9, 0, v8
	v_lshl_add_u64 v[198:199], s[18:19], 0, v[4:5]
	v_readlane_b32 s18, v254, 39
	s_waitcnt vmcnt(14)
	ds_write_b128 v9, v[120:123] offset:256
	v_add_u32_e32 v9, v9, v10
	s_add_u32 s18, s18, s30
	v_readlane_b32 s19, v254, 56
	v_add_u32_e32 v11, 0x6400, v9
	v_add_u32_e32 v9, 0x8600, v9
	v_add3_u32 v206, v8, v10, v1
	s_addc_u32 s19, s19, s31
	v_mov_b32_e32 v14, v0
	v_mov_b32_e32 v15, v0
	s_waitcnt vmcnt(13)
	ds_write2_b64 v11, v[124:125], v[126:127] offset1:1
	v_or_b32_e32 v194, s27, v16
	v_mul_u32_u24_e32 v204, 0x190, v16
	v_mul_u32_u24_e32 v205, 0x88, v16
	v_add_u32_e32 v207, v206, v10
	v_lshl_add_u64 v[200:201], s[18:19], 0, v[2:3]
	s_waitcnt vmcnt(12)
	ds_write2_b64 v9, v[144:145], v[146:147] offset1:1
	v_mov_b32_e32 v1, v0
	v_mov_b32_e32 v2, v0
	v_mov_b32_e32 v3, v0
	v_mov_b32_e32 v4, v0
	v_mov_b32_e32 v5, v0
	v_mov_b32_e32 v6, v0
	v_mov_b32_e32 v7, v0
	v_mov_b32_e32 v8, v0
	v_mov_b32_e32 v9, v0
	v_mov_b32_e32 v10, v0
	v_mov_b32_e32 v11, v0
	v_mov_b32_e32 v12, v0
	v_mov_b32_e32 v13, v0
	v_mov_b64_e32 v[30:31], v[14:15]
	v_mov_b64_e32 v[46:47], v[14:15]
	v_mov_b64_e32 v[62:63], v[14:15]
	v_mov_b64_e32 v[78:79], v[14:15]
	v_readlane_b32 s38, v255, 28
	v_readlane_b32 s44, v255, 30
	s_mov_b32 s25, 1
	v_mov_b32_e32 v209, 0xf149f2ca
	v_mov_b32_e32 v208, 0
	s_mov_b32 s26, 63
	v_mov_b64_e32 v[28:29], v[12:13]
	v_mov_b64_e32 v[26:27], v[10:11]
	v_mov_b64_e32 v[24:25], v[8:9]
	v_mov_b64_e32 v[22:23], v[6:7]
	v_mov_b64_e32 v[20:21], v[4:5]
	v_mov_b64_e32 v[18:19], v[2:3]
	v_mov_b64_e32 v[16:17], v[0:1]
	v_mov_b64_e32 v[44:45], v[12:13]
	v_mov_b64_e32 v[42:43], v[10:11]
	v_mov_b64_e32 v[40:41], v[8:9]
	v_mov_b64_e32 v[38:39], v[6:7]
	v_mov_b64_e32 v[36:37], v[4:5]
	v_mov_b64_e32 v[34:35], v[2:3]
	v_mov_b64_e32 v[32:33], v[0:1]
	v_mov_b64_e32 v[60:61], v[12:13]
	v_mov_b64_e32 v[58:59], v[10:11]
	v_mov_b64_e32 v[56:57], v[8:9]
	v_mov_b64_e32 v[54:55], v[6:7]
	v_mov_b64_e32 v[52:53], v[4:5]
	v_mov_b64_e32 v[50:51], v[2:3]
	v_mov_b64_e32 v[48:49], v[0:1]
	v_mov_b64_e32 v[76:77], v[12:13]
	v_mov_b64_e32 v[74:75], v[10:11]
	v_mov_b64_e32 v[72:73], v[8:9]
	v_mov_b64_e32 v[70:71], v[6:7]
	v_mov_b64_e32 v[68:69], v[4:5]
	v_mov_b64_e32 v[66:67], v[2:3]
	v_mov_b64_e32 v[64:65], v[0:1]
	v_readlane_b32 s39, v255, 29
	v_readlane_b32 s45, v255, 31
	v_readlane_b32 s42, v255, 32
	s_waitcnt vmcnt(0) lgkmcnt(0)
	s_barrier
	s_branch .LBB0_461
